# final RMSNorm loop: prefetch distance 2 (two rows of loads in flight per wave), counted vmcnt(10) waits
# baseline (speedup 1.0000x reference)
; __global__ void __launch_bounds__(NTHREADS, 2) mk_fwd(Args a) {
;     ...
;     {
;         const float* ss6 = ssp + (size_t)6 * SSP_STRIDE;
;         const bool local = bst[3] != 0u; const int xq = (int)bar.x, rank = (int)bst[2], nl = G / 8;
;         const int fn_first = local ? xq * SEQ + rank * NWAVES : vcu * NWAVES, fn_stride = (local ? nl : G) * NWAVES, fn_end = local ? (xq + 1) * SEQ : M;
;         f32x4 gv[2][2];
; #pragma unroll
;         for (int p = 0; p < 2; ++p) { gv[p][0] = *(const f32x4*)(P.final_g + p * 512 + lane * 8); gv[p][1] = *(const f32x4*)(P.final_g + p * 512 + lane * 8 + 4); }
;         for (int m = fn_first + wave; m < fn_end; m += fn_stride) {
;             const float rs = row_rstd(ss6, m);
; #pragma unroll
;             for (int p = 0; p < 2; ++p) {
;                 const u32x4 w = *(const u32x4*)(xb + (size_t)m * D + p * 512 + lane * 8);
;                 const f32x4 v0 = (f32x4){__uint_as_float(w.x << 16), __uint_as_float(w.x & 0xffff0000u), __uint_as_float(w.y << 16), __uint_as_float(w.y & 0xffff0000u)};
;                 const f32x4 v1 = (f32x4){__uint_as_float(w.z << 16), __uint_as_float(w.z & 0xffff0000u), __uint_as_float(w.w << 16), __uint_as_float(w.w & 0xffff0000u)};
;                 float* o = P.out + (size_t)m * D + p * 512 + lane * 8;
;                 __builtin_nontemporal_store(v0 * rs * gv[p][0], (f32x4*)o); __builtin_nontemporal_store(v1 * rs * gv[p][1], (f32x4*)(o + 4));
;             }
;         }
.LBB0_319:
	s_add_i32 s0, 0, 0x23ffc
	v_mov_b32_e32 v0, s0
	s_add_i32 s0, 0, 0x23ff8
	v_mov_b32_e32 v1, s0
	ds_read_b32 v0, v0
	ds_read_b32 v1, v1
	v_readlane_b32 s1, v253, 47
	s_add_i32 s2, s1, 0x1000
	s_waitcnt lgkmcnt(0)
	v_readfirstlane_b32 s0, v1
	s_lshl_b32 s0, s0, 3
	s_add_i32 s3, s0, s1
	v_readfirstlane_b32 s0, v0
	s_cmp_eq_u32 s0, 0
	s_cselect_b64 vcc, -1, 0
	s_and_b64 s[0:1], vcc, exec
	v_readlane_b32 s0, v253, 41
	s_cselect_b32 s1, s0, s3
	s_cselect_b32 s6, 0x8000, s2
	v_readlane_b32 s2, v255, 25
	s_add_i32 s0, s1, s2
	s_cmp_lt_i32 s0, s6
	s_cbranch_scc0 .LBB0_322
	v_readlane_b32 s8, v253, 2
	v_lshlrev_b32_e32 v20, 5, v232
	v_readlane_b32 s12, v253, 6
	v_readlane_b32 s13, v253, 7
	s_nop 4
	global_load_dwordx4 v[0:3], v20, s[12:13] offset:16
	global_load_dwordx4 v[4:7], v20, s[12:13]
	global_load_dwordx4 v[8:11], v20, s[12:13] offset:2064
	global_load_dwordx4 v[12:15], v20, s[12:13] offset:2048
	s_mov_b64 s[4:5], s[12:13]
	v_readlane_b32 s14, v253, 8
	v_readlane_b32 s15, v253, 9
	v_readlane_b32 s16, v253, 10
	v_readlane_b32 s17, v253, 11
	v_readlane_b32 s18, v253, 12
	v_readlane_b32 s19, v253, 13
	v_readlane_b32 s20, v253, 14
	v_readlane_b32 s21, v253, 15
	v_readlane_b32 s22, v253, 16
	v_readlane_b32 s23, v253, 17
	s_ashr_i32 s3, s1, 31
	s_ashr_i32 s4, s2, 31
	s_add_u32 s2, s1, s2
	v_readlane_b32 s12, v253, 18
	v_readlane_b32 s9, v253, 3
	s_addc_u32 s3, s3, s4
	v_readlane_b32 s14, v253, 20
	v_readlane_b32 s15, v253, 21
	v_readlane_b32 s26, v253, 32
	v_readlane_b32 s27, v253, 33
	v_mov_b32_e32 v16, s90
	s_lshl_b64 s[4:5], s[2:3], 6
	s_lshl_b64 s[8:9], s[2:3], 12
	s_mov_b64 s[14:15], s[26:27]
	v_cndmask_b32_e32 v16, v233, v16, vcc
	s_add_u32 s8, s14, s8
	v_lshlrev_b32_e32 v16, 3, v16
	v_mov_b32_e32 v21, 0
	s_addc_u32 s9, s15, s9
	v_ashrrev_i32_e32 v17, 31, v16
	v_lshl_add_u64 v[20:21], s[8:9], 0, v[20:21]
	s_mov_b64 s[8:9], 0x810
	s_lshl_b64 s[2:3], s[2:3], 11
	v_lshlrev_b64 v[18:19], 6, v[16:17]
	v_lshl_add_u64 v[20:21], v[20:21], 0, s[8:9]
	v_lshlrev_b64 v[22:23], 12, v[16:17]
	v_lshl_or_b32 v24, v232, 4, s2
	v_mov_b32_e32 v25, s3
	v_lshlrev_b64 v[26:27], 11, v[16:17]
	s_mov_b64 s[2:3], 0
	v_mov_b64_e32 v[28:29], s[4:5]
	v_mov_b32_e32 v17, s0
	s_mov_b64 s[4:5], 0xc00000
	v_mov_b32_e32 v30, 0x358637bd
	s_mov_b32 s7, 0x800000
	s_mov_b32 s8, 0x6200000
	v_readlane_b32 s10, v253, 4
	v_readlane_b32 s11, v253, 5
	v_readlane_b32 s13, v253, 19
	v_readlane_b32 s16, v253, 22
	v_readlane_b32 s17, v253, 23
	v_readlane_b32 s18, v253, 24
	v_readlane_b32 s19, v253, 25
	v_readlane_b32 s20, v253, 26
	v_readlane_b32 s21, v253, 27
	v_readlane_b32 s22, v253, 28
	v_readlane_b32 s23, v253, 29
	v_readlane_b32 s24, v253, 30
	v_readlane_b32 s25, v253, 31
	s_mov_b32 s9, 0
	v_lshl_add_u64 v[52:53], s[88:89], 0, v[28:29]
	v_lshl_add_u64 v[56:57], s[88:89], 0, v[24:25]
	v_lshl_add_u64 v[52:53], v[52:53], 0, s[4:5]
	v_lshl_add_u64 v[56:57], v[56:57], 0, s[8:9]
	global_load_dwordx4 v[32:35], v[52:53], off offset:32
	global_load_dwordx4 v[36:39], v[52:53], off offset:16
	global_load_dwordx4 v[40:43], v[52:53], off
	global_load_dwordx4 v[44:47], v[52:53], off offset:48
	global_load_dwordx4 v[48:51], v[56:57], off nt
	global_load_dwordx4 v[60:63], v[56:57], off offset:1024 nt
	v_mov_b32_e32 v80, v20
	v_mov_b32_e32 v81, v21
	v_add_u32_e32 v17, v17, v16
	v_lshl_add_u64 v[28:29], v[28:29], 0, v[18:19]
	v_lshl_add_u64 v[24:25], v[24:25], 0, v[26:27]
	v_lshl_add_u64 v[20:21], v[20:21], 0, v[22:23]
	v_cmp_gt_i32_e32 vcc, s6, v17
	s_cbranch_vccz .Lmy_fn_tailA
	v_lshl_add_u64 v[52:53], s[88:89], 0, v[28:29]
	v_lshl_add_u64 v[56:57], s[88:89], 0, v[24:25]
	v_lshl_add_u64 v[52:53], v[52:53], 0, s[4:5]
	v_lshl_add_u64 v[56:57], v[56:57], 0, s[8:9]
	global_load_dwordx4 v[100:103], v[52:53], off offset:32
	global_load_dwordx4 v[104:107], v[52:53], off offset:16
	global_load_dwordx4 v[108:111], v[52:53], off
	global_load_dwordx4 v[112:115], v[52:53], off offset:48
	global_load_dwordx4 v[116:119], v[56:57], off nt
	global_load_dwordx4 v[120:123], v[56:57], off offset:1024 nt
	v_mov_b32_e32 v82, v20
	v_mov_b32_e32 v83, v21
	v_add_u32_e32 v17, v17, v16
	v_lshl_add_u64 v[28:29], v[28:29], 0, v[18:19]
	v_lshl_add_u64 v[24:25], v[24:25], 0, v[26:27]
	v_lshl_add_u64 v[20:21], v[20:21], 0, v[22:23]
	s_waitcnt vmcnt(6)
; __global__ void __launch_bounds__(NTHREADS, 2) mk_fwd(Args a) {
;     ...
;         for (int m = fn_first + wave; m < fn_end; m += fn_stride) {
;             const float rs = row_rstd(ss6, m);
; #pragma unroll
;             for (int p = 0; p < 2; ++p) {
;                 const u32x4 w = *(const u32x4*)(xb + (size_t)m * D + p * 512 + lane * 8);
;                 const f32x4 v0 = (f32x4){__uint_as_float(w.x << 16), __uint_as_float(w.x & 0xffff0000u), __uint_as_float(w.y << 16), __uint_as_float(w.y & 0xffff0000u)};
;                 const f32x4 v1 = (f32x4){__uint_as_float(w.z << 16), __uint_as_float(w.z & 0xffff0000u), __uint_as_float(w.w << 16), __uint_as_float(w.w & 0xffff0000u)};
;                 float* o = P.out + (size_t)m * D + p * 512 + lane * 8;
;                 __builtin_nontemporal_store(v0 * rs * gv[p][0], (f32x4*)o); __builtin_nontemporal_store(v1 * rs * gv[p][1], (f32x4*)(o + 4));
;             }
;         }
.Lmy_fn_loop:
	s_waitcnt vmcnt(10)
	v_pk_add_f32 v[38:39], v[42:43], v[38:39]
	v_pk_add_f32 v[36:37], v[40:41], v[36:37]
	v_pk_add_f32 v[34:35], v[34:35], v[46:47]
	v_pk_add_f32 v[32:33], v[32:33], v[44:45]
	v_pk_add_f32 v[34:35], v[38:39], v[34:35]
	v_pk_add_f32 v[32:33], v[36:37], v[32:33]
	v_lshlrev_b32_e32 v64, 16, v48
	v_pk_mov_b32 v[36:37], v[32:33], v[34:35] op_sel:[1,0]
	v_mov_b32_e32 v33, v35
	v_pk_add_f32 v[32:33], v[36:37], v[32:33]
	v_and_b32_e32 v65, 0xffff0000, v48
	v_add_f32_e32 v31, v32, v33
	v_fmamk_f32 v31, v31, 0x3a800000, v30
	v_mul_f32_e32 v32, 0x4b800000, v31
	v_cmp_gt_f32_e32 vcc, s7, v31
	v_lshlrev_b32_e32 v66, 16, v49
	v_and_b32_e32 v67, 0xffff0000, v49
	v_cndmask_b32_e32 v31, v31, v32, vcc
	v_rsq_f32_e32 v31, v31
	v_lshlrev_b32_e32 v68, 16, v50
	v_and_b32_e32 v69, 0xffff0000, v50
	v_lshlrev_b32_e32 v70, 16, v51
	v_mul_f32_e32 v32, 0x45800000, v31
	v_cndmask_b32_e32 v58, v31, v32, vcc
	v_and_b32_e32 v71, 0xffff0000, v51
	v_lshlrev_b32_e32 v72, 16, v60
	v_and_b32_e32 v73, 0xffff0000, v60
	v_lshlrev_b32_e32 v74, 16, v61
	v_and_b32_e32 v75, 0xffff0000, v61
	v_lshlrev_b32_e32 v76, 16, v62
	v_and_b32_e32 v77, 0xffff0000, v62
	v_lshlrev_b32_e32 v78, 16, v63
	v_and_b32_e32 v79, 0xffff0000, v63
	v_pk_mul_f32 v[64:65], v[58:59], v[64:65] op_sel_hi:[0,1]
	v_pk_mul_f32 v[66:67], v[58:59], v[66:67] op_sel_hi:[0,1]
	v_pk_mul_f32 v[68:69], v[58:59], v[68:69] op_sel_hi:[0,1]
	v_pk_mul_f32 v[70:71], v[58:59], v[70:71] op_sel_hi:[0,1]
	v_pk_mul_f32 v[72:73], v[58:59], v[72:73] op_sel_hi:[0,1]
	v_pk_mul_f32 v[74:75], v[58:59], v[74:75] op_sel_hi:[0,1]
	v_pk_mul_f32 v[76:77], v[58:59], v[76:77] op_sel_hi:[0,1]
	v_pk_mul_f32 v[78:79], v[58:59], v[78:79] op_sel_hi:[0,1]
	v_pk_mul_f32 v[64:65], v[4:5], v[64:65]
	v_pk_mul_f32 v[66:67], v[6:7], v[66:67]
	v_pk_mul_f32 v[68:69], v[0:1], v[68:69]
	v_pk_mul_f32 v[70:71], v[2:3], v[70:71]
	v_pk_mul_f32 v[72:73], v[12:13], v[72:73]
	v_pk_mul_f32 v[74:75], v[14:15], v[74:75]
	v_pk_mul_f32 v[76:77], v[8:9], v[76:77]
	v_pk_mul_f32 v[78:79], v[10:11], v[78:79]
	global_store_dwordx4 v[80:81], v[64:67], off offset:-2064 nt
	global_store_dwordx4 v[80:81], v[68:71], off offset:-2048 nt
	global_store_dwordx4 v[80:81], v[72:75], off offset:-16 nt
	global_store_dwordx4 v[80:81], v[76:79], off nt
	v_cmp_gt_i32_e32 vcc, s6, v17
	s_cbranch_vccz .Lmy_fn_tailB
	v_lshl_add_u64 v[52:53], s[88:89], 0, v[28:29]
	v_lshl_add_u64 v[56:57], s[88:89], 0, v[24:25]
	v_lshl_add_u64 v[52:53], v[52:53], 0, s[4:5]
	v_lshl_add_u64 v[56:57], v[56:57], 0, s[8:9]
	global_load_dwordx4 v[32:35], v[52:53], off offset:32
	global_load_dwordx4 v[36:39], v[52:53], off offset:16
	global_load_dwordx4 v[40:43], v[52:53], off
	global_load_dwordx4 v[44:47], v[52:53], off offset:48
	global_load_dwordx4 v[48:51], v[56:57], off nt
	global_load_dwordx4 v[60:63], v[56:57], off offset:1024 nt
	v_mov_b32_e32 v80, v20
	v_mov_b32_e32 v81, v21
	v_add_u32_e32 v17, v17, v16
	v_lshl_add_u64 v[28:29], v[28:29], 0, v[18:19]
	v_lshl_add_u64 v[24:25], v[24:25], 0, v[26:27]
	v_lshl_add_u64 v[20:21], v[20:21], 0, v[22:23]
	s_waitcnt vmcnt(10)
	v_pk_add_f32 v[106:107], v[110:111], v[106:107]
	v_pk_add_f32 v[104:105], v[108:109], v[104:105]
	v_pk_add_f32 v[102:103], v[102:103], v[114:115]
	v_pk_add_f32 v[100:101], v[100:101], v[112:113]
	v_pk_add_f32 v[102:103], v[106:107], v[102:103]
	v_pk_add_f32 v[100:101], v[104:105], v[100:101]
	v_lshlrev_b32_e32 v64, 16, v116
	v_pk_mov_b32 v[104:105], v[100:101], v[102:103] op_sel:[1,0]
	v_mov_b32_e32 v101, v103
	v_pk_add_f32 v[100:101], v[104:105], v[100:101]
	v_and_b32_e32 v65, 0xffff0000, v116
	v_add_f32_e32 v31, v100, v101
	v_fmamk_f32 v31, v31, 0x3a800000, v30
	v_mul_f32_e32 v100, 0x4b800000, v31
	v_cmp_gt_f32_e32 vcc, s7, v31
	v_lshlrev_b32_e32 v66, 16, v117
	v_and_b32_e32 v67, 0xffff0000, v117
	v_cndmask_b32_e32 v31, v31, v100, vcc
	v_rsq_f32_e32 v31, v31
	v_lshlrev_b32_e32 v68, 16, v118
	v_and_b32_e32 v69, 0xffff0000, v118
	v_lshlrev_b32_e32 v70, 16, v119
	v_mul_f32_e32 v100, 0x45800000, v31
	v_cndmask_b32_e32 v58, v31, v100, vcc
	v_and_b32_e32 v71, 0xffff0000, v119
	v_lshlrev_b32_e32 v72, 16, v120
	v_and_b32_e32 v73, 0xffff0000, v120
	v_lshlrev_b32_e32 v74, 16, v121
	v_and_b32_e32 v75, 0xffff0000, v121
	v_lshlrev_b32_e32 v76, 16, v122
	v_and_b32_e32 v77, 0xffff0000, v122
	v_lshlrev_b32_e32 v78, 16, v123
	v_and_b32_e32 v79, 0xffff0000, v123
	v_pk_mul_f32 v[64:65], v[58:59], v[64:65] op_sel_hi:[0,1]
	v_pk_mul_f32 v[66:67], v[58:59], v[66:67] op_sel_hi:[0,1]
	v_pk_mul_f32 v[68:69], v[58:59], v[68:69] op_sel_hi:[0,1]
	v_pk_mul_f32 v[70:71], v[58:59], v[70:71] op_sel_hi:[0,1]
	v_pk_mul_f32 v[72:73], v[58:59], v[72:73] op_sel_hi:[0,1]
	v_pk_mul_f32 v[74:75], v[58:59], v[74:75] op_sel_hi:[0,1]
	v_pk_mul_f32 v[76:77], v[58:59], v[76:77] op_sel_hi:[0,1]
	v_pk_mul_f32 v[78:79], v[58:59], v[78:79] op_sel_hi:[0,1]
	v_pk_mul_f32 v[64:65], v[4:5], v[64:65]
	v_pk_mul_f32 v[66:67], v[6:7], v[66:67]
	v_pk_mul_f32 v[68:69], v[0:1], v[68:69]
	v_pk_mul_f32 v[70:71], v[2:3], v[70:71]
	v_pk_mul_f32 v[72:73], v[12:13], v[72:73]
	v_pk_mul_f32 v[74:75], v[14:15], v[74:75]
	v_pk_mul_f32 v[76:77], v[8:9], v[76:77]
	v_pk_mul_f32 v[78:79], v[10:11], v[78:79]
	global_store_dwordx4 v[82:83], v[64:67], off offset:-2064 nt
	global_store_dwordx4 v[82:83], v[68:71], off offset:-2048 nt
	global_store_dwordx4 v[82:83], v[72:75], off offset:-16 nt
	global_store_dwordx4 v[82:83], v[76:79], off nt
	v_cmp_gt_i32_e32 vcc, s6, v17
	s_cbranch_vccz .Lmy_fn_tailA
	v_lshl_add_u64 v[52:53], s[88:89], 0, v[28:29]
	v_lshl_add_u64 v[56:57], s[88:89], 0, v[24:25]
	v_lshl_add_u64 v[52:53], v[52:53], 0, s[4:5]
	v_lshl_add_u64 v[56:57], v[56:57], 0, s[8:9]
	global_load_dwordx4 v[100:103], v[52:53], off offset:32
	global_load_dwordx4 v[104:107], v[52:53], off offset:16
	global_load_dwordx4 v[108:111], v[52:53], off
	global_load_dwordx4 v[112:115], v[52:53], off offset:48
	global_load_dwordx4 v[116:119], v[56:57], off nt
	global_load_dwordx4 v[120:123], v[56:57], off offset:1024 nt
	v_mov_b32_e32 v82, v20
	v_mov_b32_e32 v83, v21
	v_add_u32_e32 v17, v17, v16
	v_lshl_add_u64 v[28:29], v[28:29], 0, v[18:19]
	v_lshl_add_u64 v[24:25], v[24:25], 0, v[26:27]
	v_lshl_add_u64 v[20:21], v[20:21], 0, v[22:23]
	s_branch .Lmy_fn_loop
; __global__ void __launch_bounds__(NTHREADS, 2) mk_fwd(Args a) {
;     ...
;         for (int m = fn_first + wave; m < fn_end; m += fn_stride) {
;             const float rs = row_rstd(ss6, m);
; #pragma unroll
;             for (int p = 0; p < 2; ++p) {
;                 const u32x4 w = *(const u32x4*)(xb + (size_t)m * D + p * 512 + lane * 8);
;                 const f32x4 v0 = (f32x4){__uint_as_float(w.x << 16), __uint_as_float(w.x & 0xffff0000u), __uint_as_float(w.y << 16), __uint_as_float(w.y & 0xffff0000u)};
;                 const f32x4 v1 = (f32x4){__uint_as_float(w.z << 16), __uint_as_float(w.z & 0xffff0000u), __uint_as_float(w.w << 16), __uint_as_float(w.w & 0xffff0000u)};
;                 float* o = P.out + (size_t)m * D + p * 512 + lane * 8;
;                 __builtin_nontemporal_store(v0 * rs * gv[p][0], (f32x4*)o); __builtin_nontemporal_store(v1 * rs * gv[p][1], (f32x4*)(o + 4));
;             }
;         }
.Lmy_fn_tailA:
	s_waitcnt vmcnt(0)
	v_pk_add_f32 v[38:39], v[42:43], v[38:39]
	v_pk_add_f32 v[36:37], v[40:41], v[36:37]
	v_pk_add_f32 v[34:35], v[34:35], v[46:47]
	v_pk_add_f32 v[32:33], v[32:33], v[44:45]
	v_pk_add_f32 v[34:35], v[38:39], v[34:35]
	v_pk_add_f32 v[32:33], v[36:37], v[32:33]
	v_lshlrev_b32_e32 v64, 16, v48
	v_pk_mov_b32 v[36:37], v[32:33], v[34:35] op_sel:[1,0]
	v_mov_b32_e32 v33, v35
	v_pk_add_f32 v[32:33], v[36:37], v[32:33]
	v_and_b32_e32 v65, 0xffff0000, v48
	v_add_f32_e32 v31, v32, v33
	v_fmamk_f32 v31, v31, 0x3a800000, v30
	v_mul_f32_e32 v32, 0x4b800000, v31
	v_cmp_gt_f32_e32 vcc, s7, v31
	v_lshlrev_b32_e32 v66, 16, v49
	v_and_b32_e32 v67, 0xffff0000, v49
	v_cndmask_b32_e32 v31, v31, v32, vcc
	v_rsq_f32_e32 v31, v31
	v_lshlrev_b32_e32 v68, 16, v50
	v_and_b32_e32 v69, 0xffff0000, v50
	v_lshlrev_b32_e32 v70, 16, v51
	v_mul_f32_e32 v32, 0x45800000, v31
	v_cndmask_b32_e32 v58, v31, v32, vcc
	v_and_b32_e32 v71, 0xffff0000, v51
	v_lshlrev_b32_e32 v72, 16, v60
	v_and_b32_e32 v73, 0xffff0000, v60
	v_lshlrev_b32_e32 v74, 16, v61
	v_and_b32_e32 v75, 0xffff0000, v61
	v_lshlrev_b32_e32 v76, 16, v62
	v_and_b32_e32 v77, 0xffff0000, v62
	v_lshlrev_b32_e32 v78, 16, v63
	v_and_b32_e32 v79, 0xffff0000, v63
	v_pk_mul_f32 v[64:65], v[58:59], v[64:65] op_sel_hi:[0,1]
	v_pk_mul_f32 v[66:67], v[58:59], v[66:67] op_sel_hi:[0,1]
	v_pk_mul_f32 v[68:69], v[58:59], v[68:69] op_sel_hi:[0,1]
	v_pk_mul_f32 v[70:71], v[58:59], v[70:71] op_sel_hi:[0,1]
	v_pk_mul_f32 v[72:73], v[58:59], v[72:73] op_sel_hi:[0,1]
	v_pk_mul_f32 v[74:75], v[58:59], v[74:75] op_sel_hi:[0,1]
	v_pk_mul_f32 v[76:77], v[58:59], v[76:77] op_sel_hi:[0,1]
	v_pk_mul_f32 v[78:79], v[58:59], v[78:79] op_sel_hi:[0,1]
	v_pk_mul_f32 v[64:65], v[4:5], v[64:65]
	v_pk_mul_f32 v[66:67], v[6:7], v[66:67]
	v_pk_mul_f32 v[68:69], v[0:1], v[68:69]
	v_pk_mul_f32 v[70:71], v[2:3], v[70:71]
	v_pk_mul_f32 v[72:73], v[12:13], v[72:73]
	v_pk_mul_f32 v[74:75], v[14:15], v[74:75]
	v_pk_mul_f32 v[76:77], v[8:9], v[76:77]
	v_pk_mul_f32 v[78:79], v[10:11], v[78:79]
	global_store_dwordx4 v[80:81], v[64:67], off offset:-2064 nt
	global_store_dwordx4 v[80:81], v[68:71], off offset:-2048 nt
	global_store_dwordx4 v[80:81], v[72:75], off offset:-16 nt
	global_store_dwordx4 v[80:81], v[76:79], off nt
	s_branch .LBB0_322
.Lmy_fn_tailB:
	s_waitcnt vmcnt(0)
	v_pk_add_f32 v[106:107], v[110:111], v[106:107]
	v_pk_add_f32 v[104:105], v[108:109], v[104:105]
	v_pk_add_f32 v[102:103], v[102:103], v[114:115]
	v_pk_add_f32 v[100:101], v[100:101], v[112:113]
	v_pk_add_f32 v[102:103], v[106:107], v[102:103]
	v_pk_add_f32 v[100:101], v[104:105], v[100:101]
	v_lshlrev_b32_e32 v64, 16, v116
	v_pk_mov_b32 v[104:105], v[100:101], v[102:103] op_sel:[1,0]
	v_mov_b32_e32 v101, v103
	v_pk_add_f32 v[100:101], v[104:105], v[100:101]
	v_and_b32_e32 v65, 0xffff0000, v116
	v_add_f32_e32 v31, v100, v101
	v_fmamk_f32 v31, v31, 0x3a800000, v30
	v_mul_f32_e32 v100, 0x4b800000, v31
	v_cmp_gt_f32_e32 vcc, s7, v31
	v_lshlrev_b32_e32 v66, 16, v117
	v_and_b32_e32 v67, 0xffff0000, v117
	v_cndmask_b32_e32 v31, v31, v100, vcc
	v_rsq_f32_e32 v31, v31
	v_lshlrev_b32_e32 v68, 16, v118
	v_and_b32_e32 v69, 0xffff0000, v118
	v_lshlrev_b32_e32 v70, 16, v119
	v_mul_f32_e32 v100, 0x45800000, v31
	v_cndmask_b32_e32 v58, v31, v100, vcc
	v_and_b32_e32 v71, 0xffff0000, v119
	v_lshlrev_b32_e32 v72, 16, v120
	v_and_b32_e32 v73, 0xffff0000, v120
	v_lshlrev_b32_e32 v74, 16, v121
	v_and_b32_e32 v75, 0xffff0000, v121
	v_lshlrev_b32_e32 v76, 16, v122
	v_and_b32_e32 v77, 0xffff0000, v122
	v_lshlrev_b32_e32 v78, 16, v123
	v_and_b32_e32 v79, 0xffff0000, v123
	v_pk_mul_f32 v[64:65], v[58:59], v[64:65] op_sel_hi:[0,1]
	v_pk_mul_f32 v[66:67], v[58:59], v[66:67] op_sel_hi:[0,1]
	v_pk_mul_f32 v[68:69], v[58:59], v[68:69] op_sel_hi:[0,1]
	v_pk_mul_f32 v[70:71], v[58:59], v[70:71] op_sel_hi:[0,1]
	v_pk_mul_f32 v[72:73], v[58:59], v[72:73] op_sel_hi:[0,1]
	v_pk_mul_f32 v[74:75], v[58:59], v[74:75] op_sel_hi:[0,1]
	v_pk_mul_f32 v[76:77], v[58:59], v[76:77] op_sel_hi:[0,1]
	v_pk_mul_f32 v[78:79], v[58:59], v[78:79] op_sel_hi:[0,1]
	v_pk_mul_f32 v[64:65], v[4:5], v[64:65]
	v_pk_mul_f32 v[66:67], v[6:7], v[66:67]
	v_pk_mul_f32 v[68:69], v[0:1], v[68:69]
	v_pk_mul_f32 v[70:71], v[2:3], v[70:71]
	v_pk_mul_f32 v[72:73], v[12:13], v[72:73]
	v_pk_mul_f32 v[74:75], v[14:15], v[74:75]
	v_pk_mul_f32 v[76:77], v[8:9], v[76:77]
	v_pk_mul_f32 v[78:79], v[10:11], v[78:79]
	global_store_dwordx4 v[82:83], v[64:67], off offset:-2064 nt
	global_store_dwordx4 v[82:83], v[68:71], off offset:-2048 nt
	global_store_dwordx4 v[82:83], v[72:75], off offset:-16 nt
	global_store_dwordx4 v[82:83], v[76:79], off nt
